# LQ+D4: diff loop next-tile LDS store and next-next-tile global loads issued piecewise between the PV MFMAs (instead of a burst at the loop top)
# speedup vs baseline: 1.0077x; 1.0077x over previous
.LBB0_696:
	s_add_i32 s1, s0, 1
	s_cmp_lg_u32 s0, 2
	s_cselect_b32 s9, s1, 0
.LBB0_700:
	s_cmp_gt_i32 s7, s5
	s_waitcnt lgkmcnt(0)
	s_barrier
	s_cbranch_scc1 .Ld4_inactive
	s_mul_i32 s14, s0, 0x4a00
	v_add_u32_e32 v0, s14, v148
	v_add3_u32 v0, v0, v130, v132
	ds_read_b128 v[2:5], v0
	ds_read_b128 v[236:239], v0 offset:4608
	ds_read_b128 v[240:243], v0 offset:32
	ds_read_b128 v[244:247], v0 offset:4640
	s_add_i32 s0, s7, 63
	v_cmp_le_i32_e32 vcc, s0, v128
	s_cmp_eq_u64 vcc, exec
	s_waitcnt lgkmcnt(3)
	v_mfma_f32_32x32x16_bf16 v[80:95], v[2:5], v[96:99], v[48:63]
	s_waitcnt lgkmcnt(2)
	v_mfma_f32_32x32x16_bf16 v[64:79], v[236:239], v[96:99], v[48:63]
	s_waitcnt lgkmcnt(1)
	v_mfma_f32_32x32x16_bf16 v[80:95], v[240:243], v[100:103], v[80:95]
	s_waitcnt lgkmcnt(0)
	v_mfma_f32_32x32x16_bf16 v[64:79], v[244:247], v[100:103], v[64:79]
	s_cbranch_scc1 .LBB0_705
	v_add_u32_e32 v0, s7, v125
	v_cmp_lt_i32_e32 vcc, v0, v128
	v_add_u32_e32 v2, 2, v0
	s_nop 4
	v_cndmask_b32_e32 v81, v169, v81, vcc
	v_cmp_le_i32_e32 vcc, v0, v128
	s_nop 1
	v_cndmask_b32_e32 v80, v169, v80, vcc
	v_cmp_le_i32_e32 vcc, v2, v128
	v_add_u32_e32 v2, 3, v0
	s_nop 0
	v_cndmask_b32_e32 v82, v169, v82, vcc
	v_cmp_le_i32_e32 vcc, v2, v128
	v_add_u32_e32 v2, 8, v0
	s_nop 0
	v_cndmask_b32_e32 v83, v169, v83, vcc
	v_cmp_le_i32_e32 vcc, v2, v128
	v_add_u32_e32 v2, 9, v0
	s_nop 0
	v_cndmask_b32_e32 v84, v169, v84, vcc
	v_cmp_le_i32_e32 vcc, v2, v128
	v_add_u32_e32 v2, 10, v0
	s_nop 0
	v_cndmask_b32_e32 v85, v169, v85, vcc
	v_cmp_le_i32_e32 vcc, v2, v128
	v_add_u32_e32 v2, 11, v0
	s_nop 0
	v_cndmask_b32_e32 v86, v169, v86, vcc
	v_cmp_le_i32_e32 vcc, v2, v128
	v_add_u32_e32 v2, 16, v0
	s_nop 0
	v_cndmask_b32_e32 v87, v169, v87, vcc
	v_cmp_le_i32_e32 vcc, v2, v128
	v_add_u32_e32 v2, 17, v0
	s_nop 0
	v_cndmask_b32_e32 v88, v169, v88, vcc
	v_cmp_le_i32_e32 vcc, v2, v128
	v_add_u32_e32 v2, 18, v0
	s_nop 0
	v_cndmask_b32_e32 v89, v169, v89, vcc
	v_cmp_le_i32_e32 vcc, v2, v128
	v_add_u32_e32 v2, 19, v0
	s_nop 0
	v_cndmask_b32_e32 v90, v169, v90, vcc
	v_cmp_le_i32_e32 vcc, v2, v128
	v_add_u32_e32 v2, 24, v0
	s_nop 0
	v_cndmask_b32_e32 v91, v169, v91, vcc
	v_cmp_le_i32_e32 vcc, v2, v128
	v_add_u32_e32 v2, 25, v0
	s_nop 0
	v_cndmask_b32_e32 v92, v169, v92, vcc
	v_cmp_le_i32_e32 vcc, v2, v128
	v_add_u32_e32 v2, 26, v0
	s_nop 0
	v_cndmask_b32_e32 v93, v169, v93, vcc
	v_cmp_le_i32_e32 vcc, v2, v128
	v_add_u32_e32 v2, 27, v0
	s_nop 0
	v_cndmask_b32_e32 v94, v169, v94, vcc
	v_cmp_le_i32_e32 vcc, v2, v128
	v_add_u32_e32 v2, 32, v0
	s_nop 0
	v_cndmask_b32_e32 v95, v169, v95, vcc
	v_cmp_le_i32_e32 vcc, v2, v128
	v_add_u32_e32 v2, 33, v0
	s_nop 0
	v_cndmask_b32_e32 v64, v169, v64, vcc
	v_cmp_le_i32_e32 vcc, v2, v128
	v_add_u32_e32 v2, 34, v0
	s_nop 0
	v_cndmask_b32_e32 v65, v169, v65, vcc
	v_cmp_le_i32_e32 vcc, v2, v128
	v_add_u32_e32 v2, 35, v0
	s_nop 0
	v_cndmask_b32_e32 v66, v169, v66, vcc
	v_cmp_le_i32_e32 vcc, v2, v128
	v_add_u32_e32 v2, 40, v0
	s_nop 0
	v_cndmask_b32_e32 v67, v169, v67, vcc
	v_cmp_le_i32_e32 vcc, v2, v128
	v_add_u32_e32 v2, 41, v0
	s_nop 0
	v_cndmask_b32_e32 v68, v169, v68, vcc
	v_cmp_le_i32_e32 vcc, v2, v128
	v_add_u32_e32 v2, 42, v0
	s_nop 0
	v_cndmask_b32_e32 v69, v169, v69, vcc
	v_cmp_le_i32_e32 vcc, v2, v128
	v_add_u32_e32 v2, 43, v0
	s_nop 0
	v_cndmask_b32_e32 v70, v169, v70, vcc
	v_cmp_le_i32_e32 vcc, v2, v128
	v_add_u32_e32 v2, 48, v0
	s_nop 0
	v_cndmask_b32_e32 v71, v169, v71, vcc
	v_cmp_le_i32_e32 vcc, v2, v128
	v_add_u32_e32 v2, 49, v0
	s_nop 0
	v_cndmask_b32_e32 v72, v169, v72, vcc
	v_cmp_le_i32_e32 vcc, v2, v128
	v_add_u32_e32 v2, 50, v0
	s_nop 0
	v_cndmask_b32_e32 v73, v169, v73, vcc
	v_cmp_le_i32_e32 vcc, v2, v128
	v_add_u32_e32 v2, 51, v0
	s_nop 0
	v_cndmask_b32_e32 v74, v169, v74, vcc
	v_cmp_le_i32_e32 vcc, v2, v128
	v_add_u32_e32 v2, 56, v0
	s_nop 0
	v_cndmask_b32_e32 v75, v169, v75, vcc
	v_cmp_le_i32_e32 vcc, v2, v128
	v_add_u32_e32 v2, 57, v0
	s_nop 0
	v_cndmask_b32_e32 v76, v169, v76, vcc
	v_cmp_le_i32_e32 vcc, v2, v128
	v_add_u32_e32 v2, 58, v0
	v_add_u32_e32 v0, 59, v0
	v_cndmask_b32_e32 v77, v169, v77, vcc
	v_cmp_le_i32_e32 vcc, v2, v128
	s_nop 1
	v_cndmask_b32_e32 v78, v169, v78, vcc
	v_cmp_gt_i32_e32 vcc, v0, v128
	s_and_saveexec_b64 s[0:1], vcc
	v_mov_b32_e32 v79, 0xf149f2ca
	s_or_b64 exec, exec, s[0:1]
